# GEMM phase prologues: K-tile 1 staging DMAs issued before the counted wait for K-tile 0 (vmcnt 2 -> 8 / 6)
# baseline (speedup 1.0000x reference)
.LBB0_324:
	s_bfe_u32 s58, s74, 0x20006
	s_lshl_b32 s59, s16, 6
	s_lshl_b32 s60, s58, 5
	s_cmpk_lt_u32 s74, 0x100
	s_mov_b64 s[34:35], 0x80
	s_cselect_b64 s[18:19], -1, 0
	v_lshl_add_u64 v[6:7], v[6:7], 0, s[34:35]
	s_add_i32 m0, s28, 0x18000
	s_nop 0
	global_load_lds_dwordx4 v[6:7], off
	v_lshl_add_u64 v[4:5], v[4:5], 0, s[34:35]
	s_add_i32 m0, s28, 0x1a000
	s_add_i32 s61, s28, 0x8000
	s_add_i32 s62, s28, 0xa000
	global_load_lds_dwordx4 v[4:5], off
	v_lshl_add_u64 v[2:3], v[2:3], 0, s[34:35]
	s_mov_b32 m0, s61
	s_add_u32 s10, s8, 0x40080
	global_load_lds_dwordx4 v[2:3], off
	v_lshl_add_u64 v[0:1], v[0:1], 0, s[34:35]
	s_mov_b32 m0, s62
	s_addc_u32 s11, s9, 0
	global_load_lds_dwordx4 v[0:1], off
	v_lshl_add_u64 v[0:1], s[10:11], 0, v[146:147]
	s_add_i32 m0, s28, 0x1c000
	v_lshlrev_b32_e32 v3, 6, v8
	global_load_lds_dwordx4 v[0:1], off
	v_lshl_add_u64 v[0:1], s[10:11], 0, v[150:151]
	s_add_i32 m0, s28, 0x1e000
	s_movk_i32 s10, 0x3c0
	global_load_lds_dwordx4 v[0:1], off
	s_waitcnt vmcnt(8)
	s_barrier
	v_and_b32_e32 v1, 64, v244
	v_xor_b32_e32 v0, 16, v244
	v_add_u32_e32 v1, 64, v1
	v_cmp_lt_i32_e32 vcc, v0, v1
	s_waitcnt vmcnt(6)
	s_add_i32 s63, 0, 0x10000
	s_add_i32 s64, 0, 0x14000
	v_cndmask_b32_e32 v0, v244, v0, vcc
	v_lshlrev_b32_e32 v166, 2, v0
	v_xor_b32_e32 v0, 32, v244
	v_cmp_lt_i32_e32 vcc, v0, v1
	v_and_b32_e32 v1, 0xfffffc00, v12
	v_lshl_add_u32 v2, s16, 13, v1
	v_cndmask_b32_e32 v0, v244, v0, vcc
	v_lshlrev_b32_e32 v167, 2, v0
	v_and_b32_e32 v0, 48, v8
	v_and_or_b32 v0, v3, s10, v0
	v_lshlrev_b32_e32 v3, 2, v8
	v_and_b32_e32 v3, 32, v3
	v_lshl_add_u32 v1, s58, 12, v1
	v_bitop3_b32 v2, v0, v2, v3 bitop3:0xde
	v_bitop3_b32 v168, v0, v1, v3 bitop3:0xde
	v_lshlrev_b32_e32 v0, 14, v13
	v_and_b32_e32 v0, 0xffff8000, v0
	v_lshl_add_u32 v0, v14, 11, v0
	v_and_b32_e32 v1, 1, v13
	v_lshl_or_b32 v0, v1, 6, v0
	v_lshl_add_u32 v154, v15, 1, v0
	v_lshlrev_b32_e32 v0, 14, v9
	v_and_b32_e32 v0, 0xffff8000, v0
	v_lshl_add_u32 v0, v10, 11, v0
	v_and_b32_e32 v1, 1, v9
	v_lshl_or_b32 v0, v1, 6, v0
	v_mov_b32_e32 v155, v153
	v_lshl_add_u32 v156, v11, 1, v0
	v_mov_b32_e32 v157, v153
	v_add_u32_e32 v169, s63, v168
	v_add_u32_e32 v170, s64, v168
	v_add_u32_e32 v171, 0, v2
	s_movk_i32 s65, 0x200
	s_movk_i32 s66, 0x1200
	s_movk_i32 s67, 0x5f
	s_movk_i32 s68, 0x6f
	s_movk_i32 s69, 0x7f
	s_mov_b64 s[36:37], 0xbe00000
	s_movk_i32 s70, 0xf400
	s_mov_b32 s71, 0x9c00000
	v_mov_b32_e32 v172, 0x358637bd
	s_mov_b32 s72, 0x800000
	s_add_i32 s73, 0, 0x20000
	s_mov_b64 s[38:39], 0x7800000
	s_mov_b64 s[40:41], 0x5800000
	v_mov_b32_e32 v173, 0xac00000
	v_mov_b32_e32 v174, 0x8a00000
	v_mov_b32_e32 v175, 0x1200
	v_mov_b32_e32 v176, 0x900
	v_mov_b32_e32 v177, 0x3e38aa3b
	s_mov_b32 s30, 0
	s_barrier
	s_branch .LBB0_327

.LBB0_813:
	s_bfe_u32 s26, s74, 0x20006
	s_lshl_b32 s79, s5, 6
	s_lshl_b32 s80, s26, 5
	s_cmpk_lt_u32 s74, 0x100
	s_mov_b64 s[10:11], 0x80
	s_cselect_b64 s[8:9], -1, 0
	v_lshl_add_u64 v[6:7], v[6:7], 0, s[10:11]
	s_add_i32 m0, s28, 0x18000
	s_nop 0
	global_load_lds_dwordx4 v[6:7], off
	v_lshl_add_u64 v[4:5], v[4:5], 0, s[10:11]
	s_add_i32 m0, s28, 0x1a000
	s_add_i32 s81, s28, 0x8000
	s_add_i32 s82, s28, 0xa000
	global_load_lds_dwordx4 v[4:5], off
	v_lshl_add_u64 v[2:3], v[2:3], 0, s[10:11]
	s_mov_b32 m0, s81
	s_add_u32 s12, s70, 0x40080
	global_load_lds_dwordx4 v[2:3], off
	v_lshl_add_u64 v[0:1], v[0:1], 0, s[10:11]
	s_mov_b32 m0, s82
	s_addc_u32 s13, s71, 0
	global_load_lds_dwordx4 v[0:1], off
	v_lshl_add_u64 v[0:1], s[12:13], 0, v[194:195]
	s_add_i32 m0, s28, 0x1c000
	v_and_b32_e32 v17, 64, v244
	global_load_lds_dwordx4 v[0:1], off
	v_lshl_add_u64 v[0:1], s[12:13], 0, v[198:199]
	s_add_i32 m0, s28, 0x1e000
	v_xor_b32_e32 v16, 16, v244
	global_load_lds_dwordx4 v[0:1], off
	s_waitcnt vmcnt(8)
	s_barrier
	v_add_u32_e32 v17, 64, v17
	v_cmp_lt_i32_e32 vcc, v16, v17
	v_and_b32_e32 v1, 0xfffffc00, v12
	v_lshl_add_u32 v2, s5, 13, v1
	v_cndmask_b32_e32 v0, v244, v16, vcc
	v_lshlrev_b32_e32 v226, 2, v0
	v_xor_b32_e32 v0, 32, v244
	v_cmp_lt_i32_e32 vcc, v0, v17
	v_lshlrev_b32_e32 v3, 6, v8
	s_movk_i32 s5, 0x3c0
	v_cndmask_b32_e32 v0, v244, v0, vcc
	v_lshlrev_b32_e32 v227, 2, v0
	v_and_b32_e32 v0, 48, v8
	v_and_or_b32 v0, v3, s5, v0
	v_lshlrev_b32_e32 v3, 2, v8
	v_and_b32_e32 v3, 32, v3
	v_lshl_add_u32 v1, s26, 12, v1
	v_bitop3_b32 v2, v0, v2, v3 bitop3:0xde
	v_bitop3_b32 v228, v0, v1, v3 bitop3:0xde
	v_lshlrev_b32_e32 v0, 14, v13
	v_and_b32_e32 v0, 0xffff8000, v0
	v_lshl_add_u32 v0, v14, 11, v0
	v_and_b32_e32 v1, 1, v13
	v_lshl_or_b32 v0, v1, 6, v0
	v_lshl_add_u32 v200, v15, 1, v0
	v_lshlrev_b32_e32 v0, 14, v9
	v_and_b32_e32 v0, 0xffff8000, v0
	s_waitcnt vmcnt(6)
	v_lshl_add_u32 v0, v10, 11, v0
	v_and_b32_e32 v1, 1, v9
	v_lshl_or_b32 v0, v1, 6, v0
	s_add_i32 s83, 0, 0x10000
	s_add_i32 s84, 0, 0x14000
	v_mov_b32_e32 v201, v195
	v_lshl_add_u32 v202, v11, 1, v0
	v_mov_b32_e32 v203, v195
	v_add_u32_e32 v229, s83, v228
	v_add_u32_e32 v230, s84, v228
	v_add_u32_e32 v231, 0, v2
	s_mov_b64 s[12:13], 0x2000
	s_mov_b64 s[14:15], 0x1000
	s_movk_i32 s85, 0x1000
	s_mov_b32 s86, 0x21800000
	s_mov_b64 s[16:17], 0x10000
	s_mov_b64 s[18:19], 0x10200
	s_mov_b64 s[34:35], 0x1800000
	s_lshl_b32 s87, s26, 2
	s_mov_b64 s[36:37], 0x20000
	s_mov_b32 s88, 0x20000
	s_mov_b64 s[38:39], 0x20200
	s_mov_b64 s[40:41], 0x30000
	s_mov_b64 s[42:43], 0x30200
	s_mov_b64 s[44:45], 0x80000
	s_mov_b64 s[46:47], 0x80200
	s_mov_b64 s[48:49], 0x90000
	s_mov_b64 s[50:51], 0x90200
	s_mov_b64 s[52:53], 0xa0000
	s_mov_b64 s[54:55], 0xa0200
	s_mov_b64 s[56:57], 0xb0000
	s_mov_b64 s[58:59], 0xb0200
	v_mov_b32_e32 v232, 0x21800000
	s_mov_b64 s[64:65], s[70:71]
	s_mov_b64 s[62:63], s[68:69]
	s_barrier
	s_branch .LBB0_816

.LBB0_947:
	s_lshl_b32 s7, s41, 2
	s_add_i32 s90, s7, 0
	s_lshl_b32 s7, s12, 2
	s_mov_b64 s[18:19], 0x80
	s_add_i32 s89, s7, 0
	v_lshl_add_u64 v[6:7], v[6:7], 0, s[18:19]
	s_add_i32 m0, s84, 0x18000
	s_add_i32 s88, s90, 0x20000
	s_add_i32 s89, s89, 0x20600
	s_add_i32 s90, s90, 0x20200
	global_load_lds_dwordx4 v[6:7], off
	v_lshl_add_u64 v[4:5], v[4:5], 0, s[18:19]
	s_add_i32 m0, s84, 0x1a000
	s_add_i32 s91, s84, 0x8000
	s_add_i32 s92, s84, 0xa000
	global_load_lds_dwordx4 v[4:5], off
	v_lshl_add_u64 v[2:3], v[2:3], 0, s[18:19]
	s_mov_b32 m0, s91
	s_add_u32 s26, s10, 0x40080
	global_load_lds_dwordx4 v[2:3], off
	v_lshl_add_u64 v[0:1], v[0:1], 0, s[18:19]
	s_mov_b32 m0, s92
	s_addc_u32 s27, s11, 0
	global_load_lds_dwordx4 v[0:1], off
	v_lshl_add_u64 v[0:1], s[26:27], 0, v[148:149]
	s_add_i32 m0, s84, 0x1c000
	v_ashrrev_i32_e32 v2, 6, v8
	global_load_lds_dwordx4 v[0:1], off
	v_lshl_add_u64 v[0:1], s[26:27], 0, v[152:153]
	s_add_i32 m0, s84, 0x1e000
	v_and_b32_e32 v4, 48, v8
	global_load_lds_dwordx4 v[0:1], off
	s_waitcnt vmcnt(8)
	s_barrier
	v_and_b32_e32 v0, 15, v8
	v_or_b32_e32 v1, s41, v0
	v_lshlrev_b32_e32 v3, 6, v1
	s_movk_i32 s7, 0x3c0
	v_lshlrev_b32_e32 v1, 2, v1
	v_and_or_b32 v3, v3, s7, v4
	v_lshl_add_u32 v5, v2, 10, s80
	v_and_b32_e32 v1, 32, v1
	v_bitop3_b32 v1, v3, v5, v1 bitop3:0xde
	v_lshlrev_b32_e32 v3, 2, v8
	v_lshl_or_b32 v0, v0, 6, v4
	v_add_lshl_u32 v2, v2, s79, 10
	v_and_b32_e32 v3, 32, v3
	v_bitop3_b32 v166, v0, v2, v3 bitop3:0xde
	v_lshlrev_b32_e32 v0, 14, v12
	v_and_b32_e32 v0, 0xffff8000, v0
	v_lshl_add_u32 v0, v13, 11, v0
	v_and_b32_e32 v2, 1, v12
	v_lshl_or_b32 v0, v2, 6, v0
	v_lshl_add_u32 v156, v14, 1, v0
	v_lshlrev_b32_e32 v0, 14, v9
	v_and_b32_e32 v0, 0xffff8000, v0
	s_waitcnt vmcnt(6)
	v_lshl_add_u32 v0, v10, 11, v0
	v_and_b32_e32 v2, 1, v9
	v_lshl_or_b32 v0, v2, 6, v0
	s_add_i32 s94, 0, 0x10000
	s_add_i32 s95, 0, 0x14000
	s_mov_b32 s93, 0
	v_mov_b32_e32 v157, v155
	v_lshl_add_u32 v158, v11, 1, v0
	v_mov_b32_e32 v159, v155
	v_add_u32_e32 v167, s94, v166
	v_add_u32_e32 v168, s95, v166
	v_add_u32_e32 v169, 0, v1
	v_mov_b32_e32 v170, 0x358637bd
	s_mov_b32 s96, 0x800000
	s_lshl_b32 s97, s12, 2
	s_mov_b64 s[34:35], 0x139100
	s_mov_b32 s28, 0x3e6d3388
	s_mov_b32 s36, 0x3f07dc22
	s_mov_b32 s38, 0x3f35f0e3
	s_mov_b32 s40, 0xbe11a98e
	s_mov_b32 s42, 0x3e027906
	s_mov_b64 s[44:45], 0x90
	s_mov_b64 s[46:47], 0xa0
	s_mov_b64 s[48:49], 0xb0
	v_mov_b32_e32 v0, 0xbf3a00e3
	s_mov_b64 s[56:57], s[10:11]
	s_mov_b64 s[52:53], s[8:9]
	s_barrier
	s_branch .LBB0_950

.LBB0_1285:
	s_mov_b64 s[10:11], 0x80
	v_lshl_add_u64 v[6:7], v[6:7], 0, s[10:11]
	s_add_i32 m0, s28, 0x18000
	s_nop 0
	global_load_lds_dwordx4 v[6:7], off
	v_lshl_add_u64 v[4:5], v[4:5], 0, s[10:11]
	s_add_i32 m0, s28, 0x1a000
	s_add_i32 s62, s28, 0x8000
	global_load_lds_dwordx4 v[4:5], off
	v_lshl_add_u64 v[2:3], v[2:3], 0, s[10:11]
	s_mov_b32 m0, s62
	s_add_i32 s63, s28, 0xa000
	global_load_lds_dwordx4 v[2:3], off
	v_lshl_add_u64 v[0:1], v[0:1], 0, s[10:11]
	s_mov_b32 m0, s63
	v_ashrrev_i32_e32 v2, 6, v8
	global_load_lds_dwordx4 v[0:1], off
	s_waitcnt vmcnt(6)
	s_barrier
	v_and_b32_e32 v0, 15, v8
	v_or_b32_e32 v1, s41, v0
	v_lshlrev_b32_e32 v3, 6, v1
	v_and_b32_e32 v4, 48, v8
	s_movk_i32 s6, 0x3c0
	v_lshlrev_b32_e32 v1, 2, v1
	v_and_or_b32 v3, v3, s6, v4
	v_lshl_add_u32 v5, v2, 10, s80
	v_and_b32_e32 v1, 32, v1
	v_bitop3_b32 v1, v3, v5, v1 bitop3:0xde
	v_lshlrev_b32_e32 v3, 2, v8
	v_lshl_or_b32 v0, v0, 6, v4
	v_add_lshl_u32 v2, v2, s79, 10
	v_and_b32_e32 v3, 32, v3
	v_bitop3_b32 v91, v0, v2, v3 bitop3:0xde
	v_and_b32_e32 v2, 64, v244
	v_xor_b32_e32 v0, 1, v244
	v_add_u32_e32 v2, 64, v2
	v_cmp_lt_i32_e32 vcc, v0, v2
	s_lshl_b32 s6, s12, 2
	s_add_i32 s66, 0, 0x20400
	v_cndmask_b32_e32 v0, v244, v0, vcc
	v_lshlrev_b32_e32 v92, 2, v0
	v_xor_b32_e32 v0, 2, v244
	v_cmp_lt_i32_e32 vcc, v0, v2
	s_add_i32 s64, s66, s6
	s_lshl_b32 s6, s41, 2
	v_cndmask_b32_e32 v0, v244, v0, vcc
	v_lshlrev_b32_e32 v93, 2, v0
	v_xor_b32_e32 v0, 4, v244
	v_cmp_lt_i32_e32 vcc, v0, v2
	s_waitcnt vmcnt(4)
	s_add_i32 s67, s6, 0
	s_add_i32 s68, 0, 0x10000
	v_cndmask_b32_e32 v0, v244, v0, vcc
	v_lshlrev_b32_e32 v94, 2, v0
	v_xor_b32_e32 v0, 8, v244
	v_cmp_lt_i32_e32 vcc, v0, v2
	v_and_b32_e32 v2, 1, v12
	s_add_i32 s65, s67, 0x23600
	v_cndmask_b32_e32 v0, v244, v0, vcc
	v_lshlrev_b32_e32 v95, 2, v0
	v_lshlrev_b32_e32 v0, 14, v12
	v_and_b32_e32 v0, 0xffff8000, v0
	v_lshl_add_u32 v0, v13, 11, v0
	v_lshl_or_b32 v0, v2, 6, v0
	v_lshl_add_u32 v80, v14, 1, v0
	v_lshlrev_b32_e32 v0, 14, v9
	v_and_b32_e32 v0, 0xffff8000, v0
	v_lshl_add_u32 v0, v10, 11, v0
	v_and_b32_e32 v2, 1, v9
	v_lshl_or_b32 v0, v2, 6, v0
	s_add_i32 s66, s66, s6
	s_add_i32 s67, s67, 0x23800
	v_mov_b32_e32 v81, v75
	v_lshl_add_u32 v82, v11, 1, v0
	v_mov_b32_e32 v83, v75
	v_add_u32_e32 v96, s68, v91
	v_add_u32_e32 v97, 0, v1
	s_mov_b64 s[16:17], 0x1700000
	v_mov_b32_e32 v98, 0x358637bd
	s_mov_b32 s69, 0x800000
	s_mov_b64 s[18:19], 0x8a00000
	s_movk_i32 s70, 0x7f
	s_mov_b32 s71, 0x3e6d3388
	s_mov_b32 s34, 0x3f07dc22
	s_mov_b32 s36, 0xbf3a00e3
	s_mov_b32 s38, 0x3f35f0e3
	s_mov_b32 s40, 0xbe11a98e
	s_mov_b32 s42, 0x3e027906
	s_movk_i32 s72, 0x1080
	s_lshl_b32 s43, s43, 2
	s_mov_b32 s73, 0
	s_mov_b64 s[48:49], s[56:57]
	s_mov_b64 s[46:47], s[52:53]
	s_barrier
	s_branch .LBB0_1288

.LBB0_1513:
	s_lshl_b32 s42, s10, 6
	s_lshl_b32 s13, s10, 13
	s_lshl_b32 s10, s75, 5
	s_and_b32 s43, s10, 0x60
	s_mov_b64 s[10:11], 0x80
	s_add_i32 m0, s36, 0x18000
	v_lshl_add_u64 v[6:7], v[6:7], 0, s[10:11]
	s_lshr_b32 s16, s43, 3
	global_load_lds_dwordx4 v[6:7], off
	v_lshl_add_u64 v[4:5], v[4:5], 0, s[10:11]
	s_add_i32 m0, s36, 0x1a000
	s_add_i32 s44, s36, 0x8000
	s_add_i32 s45, s36, 0xa000
	global_load_lds_dwordx4 v[4:5], off
	v_lshl_add_u64 v[0:1], v[0:1], 0, s[10:11]
	s_mov_b32 m0, s44
	s_add_u32 s14, s6, 0x40080
	global_load_lds_dwordx4 v[0:1], off
	v_lshl_add_u64 v[0:1], v[2:3], 0, s[10:11]
	s_mov_b32 m0, s45
	s_addc_u32 s15, s7, 0
	global_load_lds_dwordx4 v[0:1], off
	s_add_i32 m0, s36, 0x1c000
	v_lshl_add_u64 v[0:1], s[14:15], 0, v[212:213]
	global_load_lds_dwordx4 v[0:1], off
	v_lshl_add_u64 v[0:1], s[14:15], 0, v[208:209]
	s_add_i32 m0, s36, 0x1e000
	s_sext_i32_i8 s31, s12
	global_load_lds_dwordx4 v[0:1], off
	s_waitcnt vmcnt(8)
	s_barrier
	v_and_b32_e32 v1, 48, v9
	v_lshlrev_b32_e32 v3, 6, v9
	s_movk_i32 s12, 0x3c0
	v_ashrrev_i32_e32 v0, 6, v9
	v_and_or_b32 v1, v3, s12, v1
	v_lshlrev_b32_e32 v3, 2, v9
	v_lshl_add_u32 v2, v0, 10, s13
	v_and_b32_e32 v3, 32, v3
	v_add_lshl_u32 v0, v0, s16, 10
	v_bitop3_b32 v245, v1, v0, v3 bitop3:0xde
	v_lshlrev_b32_e32 v0, 14, v8
	v_and_b32_e32 v0, 0xffff8000, v0
	v_bitop3_b32 v2, v1, v2, v3 bitop3:0xde
	v_lshl_add_u32 v0, v10, 11, v0
	v_and_b32_e32 v1, 1, v8
	v_lshl_or_b32 v0, v1, 6, v0
	v_lshl_add_u32 v216, v11, 1, v0
	v_lshlrev_b32_e32 v0, 14, v12
	v_and_b32_e32 v0, 0xffff8000, v0
	s_waitcnt vmcnt(6)
	s_cmpk_lt_u32 s74, 0x100
	v_lshl_add_u32 v0, v13, 11, v0
	v_and_b32_e32 v1, 1, v12
	s_cselect_b64 s[12:13], -1, 0
	v_lshl_or_b32 v0, v1, 6, v0
	s_add_i32 s48, 0, 0x10000
	s_add_i32 s49, 0, 0x14000
	s_mov_b32 s46, 0x18000
	s_mov_b32 s47, 0x8000
	v_mov_b32_e32 v217, v213
	v_lshl_add_u32 v218, v14, 1, v0
	v_mov_b32_e32 v219, v213
	v_add_u32_e32 v246, s48, v245
	v_add_u32_e32 v247, s49, v245
	v_add_u32_e32 v248, 0, v2
	s_mov_b64 s[14:15], 0x102000
	s_mov_b32 s50, 0x102000
	s_mov_b64 s[16:17], 0x1000
	s_movk_i32 s51, 0x1000
	s_mov_b64 s[18:19], 0x101000
	s_mov_b32 s52, 0x101000
	s_mov_b32 s53, 0x21800000
	s_mov_b64 s[20:21], 0x1800000
	s_mov_b32 s54, 0x20000
	s_mov_b32 s55, 0x30000
	s_mov_b32 s56, 0x90000
	s_mov_b32 s57, 0xa0000
	s_mov_b32 s58, 0xb0000
	v_mov_b32_e32 v253, 0x5d800000
	s_mov_b64 s[26:27], s[6:7]
	s_mov_b64 s[24:25], s[4:5]
	s_barrier
	s_branch .LBB0_1516
